# P1 epilogue: straight-line sigmoid/silu fast paths (same per-element ops, hoisted addressing, no per-group branching), on v37
# speedup vs baseline: 1.0039x; 1.0039x over previous
; __device__ __forceinline__ float sigm(float v) { return __builtin_amdgcn_rcpf(1.f + __builtin_amdgcn_exp2f(-LOG2E * v)); }
; __device__ __forceinline__ float silu(float v) { return v * sigm(v); }
;     __device__ __forceinline__ void operator()(const f32x4 (&acc)[2][2][4][2], const pg8::Unit& u, int wr, int wc, int fr, int fq) const {
;     ...
;                 for (int bj = 0; bj < 2; ++bj) {
;                     f32x4 v0 = acc[ai][bj][m][0], v1 = acc[ai][bj][m][1];
;                     if (act == 1) {
; #pragma unroll
;                         for (int j = 0; j < 4; ++j) { v0[j] = silu(v0[j]); v1[j] = silu(v1[j]); }
;                     } else if (act == 2) {
; #pragma unroll
;                         for (int j = 0; j < 4; ++j) { v0[j] = sigm(v0[j]); v1[j] = sigm(v1[j]); }
;                     } else {
; #pragma unroll
;                         for (int j = 0; j < 4; ++j) s += v0[j] * v0[j] + v1[j] * v1[j];
.LBB0_507:
	s_and_b64 vcc, exec, s[6:7]
	s_cbranch_vccnz .Lepi1_sigm
	s_and_b64 vcc, exec, s[10:11]
	s_cbranch_vccnz .Lepi1_silu
	s_xor_b64 s[6:7], s[6:7], -1
	s_xor_b64 s[10:11], s[10:11], -1
	v_cndmask_b32_e64 v128, 0, 1, s[6:7]
	s_mov_b64 s[34:35], -1
	s_and_b64 vcc, exec, s[10:11]
	v_cmp_ne_u32_e64 s[6:7], 1, v128
	s_cbranch_vccz .LBB0_513
	s_and_b64 vcc, exec, s[6:7]
	s_cbranch_vccnz .LBB0_510
	v_pk_mul_f32 v[148:149], v[120:121], v[120:121]
	v_pk_mul_f32 v[128:129], v[122:123], v[122:123]
	v_pk_fma_f32 v[148:149], v[124:125], v[124:125], v[148:149]
	v_pk_fma_f32 v[128:129], v[126:127], v[126:127], v[128:129]
	v_add_f32_e32 v131, v148, v149
	v_add_f32_e32 v128, v128, v131
	v_add_f32_e32 v158, v129, v128
	s_mov_b64 s[34:35], 0

; __device__ __forceinline__ unsigned pk(float lo, float hi) { unsigned r; asm("s_nop 0\n\tv_cvt_pk_bf16_f32 %0, %1, %2" : "=v"(r) : "v"(lo), "v"(hi)); return r; }
; __device__ __forceinline__ float sigm(float v) { return __builtin_amdgcn_rcpf(1.f + __builtin_amdgcn_exp2f(-LOG2E * v)); }
; __device__ __forceinline__ float silu(float v) { return v * sigm(v); }
; __device__ __forceinline__ u32x4 pk8(const f32x4& a, const f32x4& b) { u32x4 w; w.x = pk(a[0], a[1]); w.y = pk(a[2], a[3]); w.z = pk(b[0], b[1]); w.w = pk(b[2], b[3]); return w; }
;     __device__ __forceinline__ void operator()(const f32x4 (&acc)[2][2][4][2], const pg8::Unit& u, int wr, int wc, int fr, int fq) const {
;     ...
;         dst += col + wc * 32 + 8 * fq;
; #pragma unroll
;         for (int ai = 0; ai < 2; ++ai)
; #pragma unroll
;             for (int m = 0; m < 4; ++m) {
;                 const int row = row0 + ai * 128 + m * 16; float s = 0.f;
; #pragma unroll
;                 for (int bj = 0; bj < 2; ++bj) {
;                     f32x4 v0 = acc[ai][bj][m][0], v1 = acc[ai][bj][m][1];
;                     if (act == 1) {
; #pragma unroll
;                         for (int j = 0; j < 4; ++j) { v0[j] = silu(v0[j]); v1[j] = silu(v1[j]); }
;                     } else if (act == 2) {
; #pragma unroll
;                         for (int j = 0; j < 4; ++j) { v0[j] = sigm(v0[j]); v1[j] = sigm(v1[j]); }
;                     } else {
; #pragma unroll
;                         for (int j = 0; j < 4; ++j) s += v0[j] * v0[j] + v1[j] * v1[j];
;                     }
;                     *(u32x4*)(dst + (size_t)row * ldc + bj * 128) = pk8(v0, v1);
.Lepi1_sigm:
	v_add_u32_e32 v128, s2, v162
	v_ashrrev_i32_e32 v129, 31, v128
	v_lshl_add_u64 v[128:129], v[128:129], 1, s[8:9]
	s_lshl_b32 s98, s46, 5
	s_mov_b32 s99, 0
	s_mul_i32 s100, s46, 0xa0
	s_mov_b32 s101, 0
	v_mad_u64_u32 v[148:149], s[2:3], s46, v130, 0
	v_lshl_add_u64 v[148:149], v[148:149], 1, v[128:129]
	v_mul_f32_e32 v166, 0xbfb8aa3b, v124
	v_mul_f32_e32 v167, 0xbfb8aa3b, v125
	v_mul_f32_e32 v168, 0xbfb8aa3b, v126
	v_mul_f32_e32 v169, 0xbfb8aa3b, v127
	v_mul_f32_e32 v170, 0xbfb8aa3b, v120
	v_mul_f32_e32 v171, 0xbfb8aa3b, v121
	v_mul_f32_e32 v172, 0xbfb8aa3b, v122
	v_mul_f32_e32 v173, 0xbfb8aa3b, v123
	v_exp_f32_e32 v166, v166
	v_exp_f32_e32 v167, v167
	v_exp_f32_e32 v168, v168
	v_exp_f32_e32 v169, v169
	v_exp_f32_e32 v170, v170
	v_exp_f32_e32 v171, v171
	v_exp_f32_e32 v172, v172
	v_exp_f32_e32 v173, v173
	v_add_f32_e32 v166, 1.0, v166
	v_add_f32_e32 v167, 1.0, v167
	v_add_f32_e32 v168, 1.0, v168
	v_add_f32_e32 v169, 1.0, v169
	v_add_f32_e32 v170, 1.0, v170
	v_add_f32_e32 v171, 1.0, v171
	v_add_f32_e32 v172, 1.0, v172
	v_add_f32_e32 v173, 1.0, v173
	v_rcp_f32_e32 v166, v166
	v_rcp_f32_e32 v167, v167
	v_rcp_f32_e32 v168, v168
	v_rcp_f32_e32 v169, v169
	v_rcp_f32_e32 v170, v170
	v_rcp_f32_e32 v171, v171
	v_rcp_f32_e32 v172, v172
	v_rcp_f32_e32 v173, v173
	s_nop 0
	v_cvt_pk_bf16_f32 v166, v166, v167
	v_cvt_pk_bf16_f32 v167, v168, v169
	v_cvt_pk_bf16_f32 v168, v170, v171
	v_cvt_pk_bf16_f32 v169, v172, v173
	global_store_dwordx4 v[148:149], v[166:169], off
	v_mul_f32_e32 v174, 0xbfb8aa3b, v116
	v_mul_f32_e32 v175, 0xbfb8aa3b, v117
	v_mul_f32_e32 v176, 0xbfb8aa3b, v118
	v_mul_f32_e32 v177, 0xbfb8aa3b, v119
	v_mul_f32_e32 v178, 0xbfb8aa3b, v112
	v_mul_f32_e32 v179, 0xbfb8aa3b, v113
	v_mul_f32_e32 v180, 0xbfb8aa3b, v114
	v_mul_f32_e32 v181, 0xbfb8aa3b, v115
	v_exp_f32_e32 v174, v174
	v_exp_f32_e32 v175, v175
	v_exp_f32_e32 v176, v176
	v_exp_f32_e32 v177, v177
	v_exp_f32_e32 v178, v178
	v_exp_f32_e32 v179, v179
	v_exp_f32_e32 v180, v180
	v_exp_f32_e32 v181, v181
	v_add_f32_e32 v174, 1.0, v174
	v_add_f32_e32 v175, 1.0, v175
	v_add_f32_e32 v176, 1.0, v176
	v_add_f32_e32 v177, 1.0, v177
	v_add_f32_e32 v178, 1.0, v178
	v_add_f32_e32 v179, 1.0, v179
	v_add_f32_e32 v180, 1.0, v180
	v_add_f32_e32 v181, 1.0, v181
	v_rcp_f32_e32 v174, v174
	v_rcp_f32_e32 v175, v175
	v_rcp_f32_e32 v176, v176
	v_rcp_f32_e32 v177, v177
	v_rcp_f32_e32 v178, v178
	v_rcp_f32_e32 v179, v179
	v_rcp_f32_e32 v180, v180
	v_rcp_f32_e32 v181, v181
	s_nop 0
	v_cvt_pk_bf16_f32 v174, v174, v175
	v_cvt_pk_bf16_f32 v175, v176, v177
	v_cvt_pk_bf16_f32 v176, v178, v179
	v_cvt_pk_bf16_f32 v177, v180, v181
	global_store_dwordx4 v[148:149], v[174:177], off offset:256
	v_lshl_add_u64 v[148:149], v[148:149], 0, s[98:99]
	v_mul_f32_e32 v166, 0xbfb8aa3b, v108
	v_mul_f32_e32 v167, 0xbfb8aa3b, v109
	v_mul_f32_e32 v168, 0xbfb8aa3b, v110
	v_mul_f32_e32 v169, 0xbfb8aa3b, v111
	v_mul_f32_e32 v170, 0xbfb8aa3b, v104
	v_mul_f32_e32 v171, 0xbfb8aa3b, v105
	v_mul_f32_e32 v172, 0xbfb8aa3b, v106
	v_mul_f32_e32 v173, 0xbfb8aa3b, v107
	v_exp_f32_e32 v166, v166
	v_exp_f32_e32 v167, v167
	v_exp_f32_e32 v168, v168
	v_exp_f32_e32 v169, v169
	v_exp_f32_e32 v170, v170
	v_exp_f32_e32 v171, v171
	v_exp_f32_e32 v172, v172
	v_exp_f32_e32 v173, v173
	v_add_f32_e32 v166, 1.0, v166
	v_add_f32_e32 v167, 1.0, v167
	v_add_f32_e32 v168, 1.0, v168
	v_add_f32_e32 v169, 1.0, v169
	v_add_f32_e32 v170, 1.0, v170
	v_add_f32_e32 v171, 1.0, v171
	v_add_f32_e32 v172, 1.0, v172
	v_add_f32_e32 v173, 1.0, v173
	v_rcp_f32_e32 v166, v166
	v_rcp_f32_e32 v167, v167
	v_rcp_f32_e32 v168, v168
	v_rcp_f32_e32 v169, v169
	v_rcp_f32_e32 v170, v170
	v_rcp_f32_e32 v171, v171
	v_rcp_f32_e32 v172, v172
	v_rcp_f32_e32 v173, v173
	s_nop 0
	v_cvt_pk_bf16_f32 v166, v166, v167
	v_cvt_pk_bf16_f32 v167, v168, v169
	v_cvt_pk_bf16_f32 v168, v170, v171
	v_cvt_pk_bf16_f32 v169, v172, v173
	global_store_dwordx4 v[148:149], v[166:169], off
	v_mul_f32_e32 v174, 0xbfb8aa3b, v100
	v_mul_f32_e32 v175, 0xbfb8aa3b, v101
	v_mul_f32_e32 v176, 0xbfb8aa3b, v102
	v_mul_f32_e32 v177, 0xbfb8aa3b, v103
	v_mul_f32_e32 v178, 0xbfb8aa3b, v96
	v_mul_f32_e32 v179, 0xbfb8aa3b, v97
	v_mul_f32_e32 v180, 0xbfb8aa3b, v98
	v_mul_f32_e32 v181, 0xbfb8aa3b, v99
	v_exp_f32_e32 v174, v174
	v_exp_f32_e32 v175, v175
	v_exp_f32_e32 v176, v176
	v_exp_f32_e32 v177, v177
	v_exp_f32_e32 v178, v178
	v_exp_f32_e32 v179, v179
	v_exp_f32_e32 v180, v180
	v_exp_f32_e32 v181, v181
	v_add_f32_e32 v174, 1.0, v174
	v_add_f32_e32 v175, 1.0, v175
	v_add_f32_e32 v176, 1.0, v176
	v_add_f32_e32 v177, 1.0, v177
	v_add_f32_e32 v178, 1.0, v178
	v_add_f32_e32 v179, 1.0, v179
	v_add_f32_e32 v180, 1.0, v180
	v_add_f32_e32 v181, 1.0, v181
	v_rcp_f32_e32 v174, v174
	v_rcp_f32_e32 v175, v175
	v_rcp_f32_e32 v176, v176
	v_rcp_f32_e32 v177, v177
	v_rcp_f32_e32 v178, v178
	v_rcp_f32_e32 v179, v179
	v_rcp_f32_e32 v180, v180
	v_rcp_f32_e32 v181, v181
	s_nop 0
	v_cvt_pk_bf16_f32 v174, v174, v175
	v_cvt_pk_bf16_f32 v175, v176, v177
	v_cvt_pk_bf16_f32 v176, v178, v179
	v_cvt_pk_bf16_f32 v177, v180, v181
	global_store_dwordx4 v[148:149], v[174:177], off offset:256
	v_lshl_add_u64 v[148:149], v[148:149], 0, s[98:99]
	v_mul_f32_e32 v166, 0xbfb8aa3b, v92
	v_mul_f32_e32 v167, 0xbfb8aa3b, v93
	v_mul_f32_e32 v168, 0xbfb8aa3b, v94
	v_mul_f32_e32 v169, 0xbfb8aa3b, v95
	v_mul_f32_e32 v170, 0xbfb8aa3b, v88
	v_mul_f32_e32 v171, 0xbfb8aa3b, v89
	v_mul_f32_e32 v172, 0xbfb8aa3b, v90
	v_mul_f32_e32 v173, 0xbfb8aa3b, v91
	v_exp_f32_e32 v166, v166
	v_exp_f32_e32 v167, v167
	v_exp_f32_e32 v168, v168
	v_exp_f32_e32 v169, v169
	v_exp_f32_e32 v170, v170
	v_exp_f32_e32 v171, v171
	v_exp_f32_e32 v172, v172
	v_exp_f32_e32 v173, v173
; __device__ __forceinline__ unsigned pk(float lo, float hi) { unsigned r; asm("s_nop 0\n\tv_cvt_pk_bf16_f32 %0, %1, %2" : "=v"(r) : "v"(lo), "v"(hi)); return r; }
; __device__ __forceinline__ float sigm(float v) { return __builtin_amdgcn_rcpf(1.f + __builtin_amdgcn_exp2f(-LOG2E * v)); }
; __device__ __forceinline__ float silu(float v) { return v * sigm(v); }
; __device__ __forceinline__ u32x4 pk8(const f32x4& a, const f32x4& b) { u32x4 w; w.x = pk(a[0], a[1]); w.y = pk(a[2], a[3]); w.z = pk(b[0], b[1]); w.w = pk(b[2], b[3]); return w; }
;     __device__ __forceinline__ void operator()(const f32x4 (&acc)[2][2][4][2], const pg8::Unit& u, int wr, int wc, int fr, int fq) const {
;     ...
;         dst += col + wc * 32 + 8 * fq;
; #pragma unroll
;         for (int ai = 0; ai < 2; ++ai)
; #pragma unroll
;             for (int m = 0; m < 4; ++m) {
;                 const int row = row0 + ai * 128 + m * 16; float s = 0.f;
; #pragma unroll
;                 for (int bj = 0; bj < 2; ++bj) {
;                     f32x4 v0 = acc[ai][bj][m][0], v1 = acc[ai][bj][m][1];
;                     if (act == 1) {
; #pragma unroll
;                         for (int j = 0; j < 4; ++j) { v0[j] = silu(v0[j]); v1[j] = silu(v1[j]); }
;                     } else if (act == 2) {
; #pragma unroll
;                         for (int j = 0; j < 4; ++j) { v0[j] = sigm(v0[j]); v1[j] = sigm(v1[j]); }
;                     } else {
; #pragma unroll
;                         for (int j = 0; j < 4; ++j) s += v0[j] * v0[j] + v1[j] * v1[j];
;                     }
;                     *(u32x4*)(dst + (size_t)row * ldc + bj * 128) = pk8(v0, v1);
	v_add_f32_e32 v166, 1.0, v166
	v_add_f32_e32 v167, 1.0, v167
	v_add_f32_e32 v168, 1.0, v168
	v_add_f32_e32 v169, 1.0, v169
	v_add_f32_e32 v170, 1.0, v170
	v_add_f32_e32 v171, 1.0, v171
	v_add_f32_e32 v172, 1.0, v172
	v_add_f32_e32 v173, 1.0, v173
	v_rcp_f32_e32 v166, v166
	v_rcp_f32_e32 v167, v167
	v_rcp_f32_e32 v168, v168
	v_rcp_f32_e32 v169, v169
	v_rcp_f32_e32 v170, v170
	v_rcp_f32_e32 v171, v171
	v_rcp_f32_e32 v172, v172
	v_rcp_f32_e32 v173, v173
	s_nop 0
	v_cvt_pk_bf16_f32 v166, v166, v167
	v_cvt_pk_bf16_f32 v167, v168, v169
	v_cvt_pk_bf16_f32 v168, v170, v171
	v_cvt_pk_bf16_f32 v169, v172, v173
	global_store_dwordx4 v[148:149], v[166:169], off
	v_mul_f32_e32 v174, 0xbfb8aa3b, v84
	v_mul_f32_e32 v175, 0xbfb8aa3b, v85
	v_mul_f32_e32 v176, 0xbfb8aa3b, v86
	v_mul_f32_e32 v177, 0xbfb8aa3b, v87
	v_mul_f32_e32 v178, 0xbfb8aa3b, v80
	v_mul_f32_e32 v179, 0xbfb8aa3b, v81
	v_mul_f32_e32 v180, 0xbfb8aa3b, v82
	v_mul_f32_e32 v181, 0xbfb8aa3b, v83
	v_exp_f32_e32 v174, v174
	v_exp_f32_e32 v175, v175
	v_exp_f32_e32 v176, v176
	v_exp_f32_e32 v177, v177
	v_exp_f32_e32 v178, v178
	v_exp_f32_e32 v179, v179
	v_exp_f32_e32 v180, v180
	v_exp_f32_e32 v181, v181
	v_add_f32_e32 v174, 1.0, v174
	v_add_f32_e32 v175, 1.0, v175
	v_add_f32_e32 v176, 1.0, v176
	v_add_f32_e32 v177, 1.0, v177
	v_add_f32_e32 v178, 1.0, v178
	v_add_f32_e32 v179, 1.0, v179
	v_add_f32_e32 v180, 1.0, v180
	v_add_f32_e32 v181, 1.0, v181
	v_rcp_f32_e32 v174, v174
	v_rcp_f32_e32 v175, v175
	v_rcp_f32_e32 v176, v176
	v_rcp_f32_e32 v177, v177
	v_rcp_f32_e32 v178, v178
	v_rcp_f32_e32 v179, v179
	v_rcp_f32_e32 v180, v180
	v_rcp_f32_e32 v181, v181
	s_nop 0
	v_cvt_pk_bf16_f32 v174, v174, v175
	v_cvt_pk_bf16_f32 v175, v176, v177
	v_cvt_pk_bf16_f32 v176, v178, v179
	v_cvt_pk_bf16_f32 v177, v180, v181
	global_store_dwordx4 v[148:149], v[174:177], off offset:256
	v_lshl_add_u64 v[148:149], v[148:149], 0, s[98:99]
	v_mul_f32_e32 v166, 0xbfb8aa3b, v76
	v_mul_f32_e32 v167, 0xbfb8aa3b, v77
	v_mul_f32_e32 v168, 0xbfb8aa3b, v78
	v_mul_f32_e32 v169, 0xbfb8aa3b, v79
	v_mul_f32_e32 v170, 0xbfb8aa3b, v72
	v_mul_f32_e32 v171, 0xbfb8aa3b, v73
	v_mul_f32_e32 v172, 0xbfb8aa3b, v74
	v_mul_f32_e32 v173, 0xbfb8aa3b, v75
	v_exp_f32_e32 v166, v166
	v_exp_f32_e32 v167, v167
	v_exp_f32_e32 v168, v168
	v_exp_f32_e32 v169, v169
	v_exp_f32_e32 v170, v170
	v_exp_f32_e32 v171, v171
	v_exp_f32_e32 v172, v172
	v_exp_f32_e32 v173, v173
	v_add_f32_e32 v166, 1.0, v166
	v_add_f32_e32 v167, 1.0, v167
	v_add_f32_e32 v168, 1.0, v168
	v_add_f32_e32 v169, 1.0, v169
	v_add_f32_e32 v170, 1.0, v170
	v_add_f32_e32 v171, 1.0, v171
	v_add_f32_e32 v172, 1.0, v172
	v_add_f32_e32 v173, 1.0, v173
	v_rcp_f32_e32 v166, v166
	v_rcp_f32_e32 v167, v167
	v_rcp_f32_e32 v168, v168
	v_rcp_f32_e32 v169, v169
	v_rcp_f32_e32 v170, v170
	v_rcp_f32_e32 v171, v171
	v_rcp_f32_e32 v172, v172
	v_rcp_f32_e32 v173, v173
	s_nop 0
	v_cvt_pk_bf16_f32 v166, v166, v167
	v_cvt_pk_bf16_f32 v167, v168, v169
	v_cvt_pk_bf16_f32 v168, v170, v171
	v_cvt_pk_bf16_f32 v169, v172, v173
	global_store_dwordx4 v[148:149], v[166:169], off
	v_mul_f32_e32 v174, 0xbfb8aa3b, v68
	v_mul_f32_e32 v175, 0xbfb8aa3b, v69
	v_mul_f32_e32 v176, 0xbfb8aa3b, v70
	v_mul_f32_e32 v177, 0xbfb8aa3b, v71
	v_mul_f32_e32 v178, 0xbfb8aa3b, v64
	v_mul_f32_e32 v179, 0xbfb8aa3b, v65
	v_mul_f32_e32 v180, 0xbfb8aa3b, v66
	v_mul_f32_e32 v181, 0xbfb8aa3b, v67
	v_exp_f32_e32 v174, v174
	v_exp_f32_e32 v175, v175
	v_exp_f32_e32 v176, v176
	v_exp_f32_e32 v177, v177
	v_exp_f32_e32 v178, v178
	v_exp_f32_e32 v179, v179
	v_exp_f32_e32 v180, v180
	v_exp_f32_e32 v181, v181
	v_add_f32_e32 v174, 1.0, v174
	v_add_f32_e32 v175, 1.0, v175
	v_add_f32_e32 v176, 1.0, v176
	v_add_f32_e32 v177, 1.0, v177
	v_add_f32_e32 v178, 1.0, v178
	v_add_f32_e32 v179, 1.0, v179
	v_add_f32_e32 v180, 1.0, v180
	v_add_f32_e32 v181, 1.0, v181
	v_rcp_f32_e32 v174, v174
	v_rcp_f32_e32 v175, v175
	v_rcp_f32_e32 v176, v176
	v_rcp_f32_e32 v177, v177
	v_rcp_f32_e32 v178, v178
	v_rcp_f32_e32 v179, v179
	v_rcp_f32_e32 v180, v180
	v_rcp_f32_e32 v181, v181
	s_nop 0
	v_cvt_pk_bf16_f32 v174, v174, v175
	v_cvt_pk_bf16_f32 v175, v176, v177
	v_cvt_pk_bf16_f32 v176, v178, v179
	v_cvt_pk_bf16_f32 v177, v180, v181
	global_store_dwordx4 v[148:149], v[174:177], off offset:256
	v_lshl_add_u64 v[148:149], v[148:149], 0, s[100:101]
	v_mul_f32_e32 v166, 0xbfb8aa3b, v60
	v_mul_f32_e32 v167, 0xbfb8aa3b, v61
	v_mul_f32_e32 v168, 0xbfb8aa3b, v62
	v_mul_f32_e32 v169, 0xbfb8aa3b, v63
	v_mul_f32_e32 v170, 0xbfb8aa3b, v56
	v_mul_f32_e32 v171, 0xbfb8aa3b, v57
	v_mul_f32_e32 v172, 0xbfb8aa3b, v58
	v_mul_f32_e32 v173, 0xbfb8aa3b, v59
	v_exp_f32_e32 v166, v166
	v_exp_f32_e32 v167, v167
	v_exp_f32_e32 v168, v168
	v_exp_f32_e32 v169, v169
	v_exp_f32_e32 v170, v170
	v_exp_f32_e32 v171, v171
	v_exp_f32_e32 v172, v172
	v_exp_f32_e32 v173, v173
	v_add_f32_e32 v166, 1.0, v166
	v_add_f32_e32 v167, 1.0, v167
	v_add_f32_e32 v168, 1.0, v168
	v_add_f32_e32 v169, 1.0, v169
	v_add_f32_e32 v170, 1.0, v170
	v_add_f32_e32 v171, 1.0, v171
	v_add_f32_e32 v172, 1.0, v172
	v_add_f32_e32 v173, 1.0, v173
	v_rcp_f32_e32 v166, v166
	v_rcp_f32_e32 v167, v167
	v_rcp_f32_e32 v168, v168
	v_rcp_f32_e32 v169, v169
	v_rcp_f32_e32 v170, v170
	v_rcp_f32_e32 v171, v171
	v_rcp_f32_e32 v172, v172
	v_rcp_f32_e32 v173, v173
	s_nop 0
	v_cvt_pk_bf16_f32 v166, v166, v167
	v_cvt_pk_bf16_f32 v167, v168, v169
	v_cvt_pk_bf16_f32 v168, v170, v171
	v_cvt_pk_bf16_f32 v169, v172, v173
	global_store_dwordx4 v[148:149], v[166:169], off
	v_mul_f32_e32 v174, 0xbfb8aa3b, v52
	v_mul_f32_e32 v175, 0xbfb8aa3b, v53
	v_mul_f32_e32 v176, 0xbfb8aa3b, v54
	v_mul_f32_e32 v177, 0xbfb8aa3b, v55
	v_mul_f32_e32 v178, 0xbfb8aa3b, v48
; __device__ __forceinline__ unsigned pk(float lo, float hi) { unsigned r; asm("s_nop 0\n\tv_cvt_pk_bf16_f32 %0, %1, %2" : "=v"(r) : "v"(lo), "v"(hi)); return r; }
; __device__ __forceinline__ float sigm(float v) { return __builtin_amdgcn_rcpf(1.f + __builtin_amdgcn_exp2f(-LOG2E * v)); }
; __device__ __forceinline__ float silu(float v) { return v * sigm(v); }
; __device__ __forceinline__ u32x4 pk8(const f32x4& a, const f32x4& b) { u32x4 w; w.x = pk(a[0], a[1]); w.y = pk(a[2], a[3]); w.z = pk(b[0], b[1]); w.w = pk(b[2], b[3]); return w; }
;     __device__ __forceinline__ void operator()(const f32x4 (&acc)[2][2][4][2], const pg8::Unit& u, int wr, int wc, int fr, int fq) const {
;     ...
;         dst += col + wc * 32 + 8 * fq;
; #pragma unroll
;         for (int ai = 0; ai < 2; ++ai)
; #pragma unroll
;             for (int m = 0; m < 4; ++m) {
;                 const int row = row0 + ai * 128 + m * 16; float s = 0.f;
; #pragma unroll
;                 for (int bj = 0; bj < 2; ++bj) {
;                     f32x4 v0 = acc[ai][bj][m][0], v1 = acc[ai][bj][m][1];
;                     if (act == 1) {
; #pragma unroll
;                         for (int j = 0; j < 4; ++j) { v0[j] = silu(v0[j]); v1[j] = silu(v1[j]); }
;                     } else if (act == 2) {
; #pragma unroll
;                         for (int j = 0; j < 4; ++j) { v0[j] = sigm(v0[j]); v1[j] = sigm(v1[j]); }
;                     } else {
; #pragma unroll
;                         for (int j = 0; j < 4; ++j) s += v0[j] * v0[j] + v1[j] * v1[j];
;                     }
;                     *(u32x4*)(dst + (size_t)row * ldc + bj * 128) = pk8(v0, v1);
	v_mul_f32_e32 v179, 0xbfb8aa3b, v49
	v_mul_f32_e32 v180, 0xbfb8aa3b, v50
	v_mul_f32_e32 v181, 0xbfb8aa3b, v51
	v_exp_f32_e32 v174, v174
	v_exp_f32_e32 v175, v175
	v_exp_f32_e32 v176, v176
	v_exp_f32_e32 v177, v177
	v_exp_f32_e32 v178, v178
	v_exp_f32_e32 v179, v179
	v_exp_f32_e32 v180, v180
	v_exp_f32_e32 v181, v181
	v_add_f32_e32 v174, 1.0, v174
	v_add_f32_e32 v175, 1.0, v175
	v_add_f32_e32 v176, 1.0, v176
	v_add_f32_e32 v177, 1.0, v177
	v_add_f32_e32 v178, 1.0, v178
	v_add_f32_e32 v179, 1.0, v179
	v_add_f32_e32 v180, 1.0, v180
	v_add_f32_e32 v181, 1.0, v181
	v_rcp_f32_e32 v174, v174
	v_rcp_f32_e32 v175, v175
	v_rcp_f32_e32 v176, v176
	v_rcp_f32_e32 v177, v177
	v_rcp_f32_e32 v178, v178
	v_rcp_f32_e32 v179, v179
	v_rcp_f32_e32 v180, v180
	v_rcp_f32_e32 v181, v181
	s_nop 0
	v_cvt_pk_bf16_f32 v174, v174, v175
	v_cvt_pk_bf16_f32 v175, v176, v177
	v_cvt_pk_bf16_f32 v176, v178, v179
	v_cvt_pk_bf16_f32 v177, v180, v181
	global_store_dwordx4 v[148:149], v[174:177], off offset:256
	v_lshl_add_u64 v[148:149], v[148:149], 0, s[98:99]
	v_mul_f32_e32 v166, 0xbfb8aa3b, v44
	v_mul_f32_e32 v167, 0xbfb8aa3b, v45
	v_mul_f32_e32 v168, 0xbfb8aa3b, v46
	v_mul_f32_e32 v169, 0xbfb8aa3b, v47
	v_mul_f32_e32 v170, 0xbfb8aa3b, v40
	v_mul_f32_e32 v171, 0xbfb8aa3b, v41
	v_mul_f32_e32 v172, 0xbfb8aa3b, v42
	v_mul_f32_e32 v173, 0xbfb8aa3b, v43
	v_exp_f32_e32 v166, v166
	v_exp_f32_e32 v167, v167
	v_exp_f32_e32 v168, v168
	v_exp_f32_e32 v169, v169
	v_exp_f32_e32 v170, v170
	v_exp_f32_e32 v171, v171
	v_exp_f32_e32 v172, v172
	v_exp_f32_e32 v173, v173
	v_add_f32_e32 v166, 1.0, v166
	v_add_f32_e32 v167, 1.0, v167
	v_add_f32_e32 v168, 1.0, v168
	v_add_f32_e32 v169, 1.0, v169
	v_add_f32_e32 v170, 1.0, v170
	v_add_f32_e32 v171, 1.0, v171
	v_add_f32_e32 v172, 1.0, v172
	v_add_f32_e32 v173, 1.0, v173
	v_rcp_f32_e32 v166, v166
	v_rcp_f32_e32 v167, v167
	v_rcp_f32_e32 v168, v168
	v_rcp_f32_e32 v169, v169
	v_rcp_f32_e32 v170, v170
	v_rcp_f32_e32 v171, v171
	v_rcp_f32_e32 v172, v172
	v_rcp_f32_e32 v173, v173
	s_nop 0
	v_cvt_pk_bf16_f32 v166, v166, v167
	v_cvt_pk_bf16_f32 v167, v168, v169
	v_cvt_pk_bf16_f32 v168, v170, v171
	v_cvt_pk_bf16_f32 v169, v172, v173
	global_store_dwordx4 v[148:149], v[166:169], off
	v_mul_f32_e32 v174, 0xbfb8aa3b, v36
	v_mul_f32_e32 v175, 0xbfb8aa3b, v37
	v_mul_f32_e32 v176, 0xbfb8aa3b, v38
	v_mul_f32_e32 v177, 0xbfb8aa3b, v39
	v_mul_f32_e32 v178, 0xbfb8aa3b, v32
	v_mul_f32_e32 v179, 0xbfb8aa3b, v33
	v_mul_f32_e32 v180, 0xbfb8aa3b, v34
	v_mul_f32_e32 v181, 0xbfb8aa3b, v35
	v_exp_f32_e32 v174, v174
	v_exp_f32_e32 v175, v175
	v_exp_f32_e32 v176, v176
	v_exp_f32_e32 v177, v177
	v_exp_f32_e32 v178, v178
	v_exp_f32_e32 v179, v179
	v_exp_f32_e32 v180, v180
	v_exp_f32_e32 v181, v181
	v_add_f32_e32 v174, 1.0, v174
	v_add_f32_e32 v175, 1.0, v175
	v_add_f32_e32 v176, 1.0, v176
	v_add_f32_e32 v177, 1.0, v177
	v_add_f32_e32 v178, 1.0, v178
	v_add_f32_e32 v179, 1.0, v179
	v_add_f32_e32 v180, 1.0, v180
	v_add_f32_e32 v181, 1.0, v181
	v_rcp_f32_e32 v174, v174
	v_rcp_f32_e32 v175, v175
	v_rcp_f32_e32 v176, v176
	v_rcp_f32_e32 v177, v177
	v_rcp_f32_e32 v178, v178
	v_rcp_f32_e32 v179, v179
	v_rcp_f32_e32 v180, v180
	v_rcp_f32_e32 v181, v181
	s_nop 0
	v_cvt_pk_bf16_f32 v174, v174, v175
	v_cvt_pk_bf16_f32 v175, v176, v177
	v_cvt_pk_bf16_f32 v176, v178, v179
	v_cvt_pk_bf16_f32 v177, v180, v181
	global_store_dwordx4 v[148:149], v[174:177], off offset:256
	v_lshl_add_u64 v[148:149], v[148:149], 0, s[98:99]
	v_mul_f32_e32 v166, 0xbfb8aa3b, v28
	v_mul_f32_e32 v167, 0xbfb8aa3b, v29
	v_mul_f32_e32 v168, 0xbfb8aa3b, v30
	v_mul_f32_e32 v169, 0xbfb8aa3b, v31
	v_mul_f32_e32 v170, 0xbfb8aa3b, v24
	v_mul_f32_e32 v171, 0xbfb8aa3b, v25
	v_mul_f32_e32 v172, 0xbfb8aa3b, v26
	v_mul_f32_e32 v173, 0xbfb8aa3b, v27
	v_exp_f32_e32 v166, v166
	v_exp_f32_e32 v167, v167
	v_exp_f32_e32 v168, v168
	v_exp_f32_e32 v169, v169
	v_exp_f32_e32 v170, v170
	v_exp_f32_e32 v171, v171
	v_exp_f32_e32 v172, v172
	v_exp_f32_e32 v173, v173
	v_add_f32_e32 v166, 1.0, v166
	v_add_f32_e32 v167, 1.0, v167
	v_add_f32_e32 v168, 1.0, v168
	v_add_f32_e32 v169, 1.0, v169
	v_add_f32_e32 v170, 1.0, v170
	v_add_f32_e32 v171, 1.0, v171
	v_add_f32_e32 v172, 1.0, v172
	v_add_f32_e32 v173, 1.0, v173
	v_rcp_f32_e32 v166, v166
	v_rcp_f32_e32 v167, v167
	v_rcp_f32_e32 v168, v168
	v_rcp_f32_e32 v169, v169
	v_rcp_f32_e32 v170, v170
	v_rcp_f32_e32 v171, v171
	v_rcp_f32_e32 v172, v172
	v_rcp_f32_e32 v173, v173
	s_nop 0
	v_cvt_pk_bf16_f32 v166, v166, v167
	v_cvt_pk_bf16_f32 v167, v168, v169
	v_cvt_pk_bf16_f32 v168, v170, v171
	v_cvt_pk_bf16_f32 v169, v172, v173
	global_store_dwordx4 v[148:149], v[166:169], off
	v_mul_f32_e32 v174, 0xbfb8aa3b, v20
	v_mul_f32_e32 v175, 0xbfb8aa3b, v21
	v_mul_f32_e32 v176, 0xbfb8aa3b, v22
	v_mul_f32_e32 v177, 0xbfb8aa3b, v23
	v_mul_f32_e32 v178, 0xbfb8aa3b, v16
	v_mul_f32_e32 v179, 0xbfb8aa3b, v17
	v_mul_f32_e32 v180, 0xbfb8aa3b, v18
	v_mul_f32_e32 v181, 0xbfb8aa3b, v19
	v_exp_f32_e32 v174, v174
	v_exp_f32_e32 v175, v175
	v_exp_f32_e32 v176, v176
	v_exp_f32_e32 v177, v177
	v_exp_f32_e32 v178, v178
	v_exp_f32_e32 v179, v179
	v_exp_f32_e32 v180, v180
	v_exp_f32_e32 v181, v181
	v_add_f32_e32 v174, 1.0, v174
	v_add_f32_e32 v175, 1.0, v175
	v_add_f32_e32 v176, 1.0, v176
	v_add_f32_e32 v177, 1.0, v177
	v_add_f32_e32 v178, 1.0, v178
	v_add_f32_e32 v179, 1.0, v179
	v_add_f32_e32 v180, 1.0, v180
	v_add_f32_e32 v181, 1.0, v181
	v_rcp_f32_e32 v174, v174
	v_rcp_f32_e32 v175, v175
	v_rcp_f32_e32 v176, v176
	v_rcp_f32_e32 v177, v177
	v_rcp_f32_e32 v178, v178
	v_rcp_f32_e32 v179, v179
	v_rcp_f32_e32 v180, v180
	v_rcp_f32_e32 v181, v181
	s_nop 0
	v_cvt_pk_bf16_f32 v174, v174, v175
	v_cvt_pk_bf16_f32 v175, v176, v177
; __device__ __forceinline__ unsigned pk(float lo, float hi) { unsigned r; asm("s_nop 0\n\tv_cvt_pk_bf16_f32 %0, %1, %2" : "=v"(r) : "v"(lo), "v"(hi)); return r; }
; __device__ __forceinline__ float sigm(float v) { return __builtin_amdgcn_rcpf(1.f + __builtin_amdgcn_exp2f(-LOG2E * v)); }
; __device__ __forceinline__ float silu(float v) { return v * sigm(v); }
; __device__ __forceinline__ u32x4 pk8(const f32x4& a, const f32x4& b) { u32x4 w; w.x = pk(a[0], a[1]); w.y = pk(a[2], a[3]); w.z = pk(b[0], b[1]); w.w = pk(b[2], b[3]); return w; }
;     __device__ __forceinline__ void operator()(const f32x4 (&acc)[2][2][4][2], const pg8::Unit& u, int wr, int wc, int fr, int fq) const {
;     ...
;         dst += col + wc * 32 + 8 * fq;
; #pragma unroll
;         for (int ai = 0; ai < 2; ++ai)
; #pragma unroll
;             for (int m = 0; m < 4; ++m) {
;                 const int row = row0 + ai * 128 + m * 16; float s = 0.f;
; #pragma unroll
;                 for (int bj = 0; bj < 2; ++bj) {
;                     f32x4 v0 = acc[ai][bj][m][0], v1 = acc[ai][bj][m][1];
;                     if (act == 1) {
; #pragma unroll
;                         for (int j = 0; j < 4; ++j) { v0[j] = silu(v0[j]); v1[j] = silu(v1[j]); }
;                     } else if (act == 2) {
; #pragma unroll
;                         for (int j = 0; j < 4; ++j) { v0[j] = sigm(v0[j]); v1[j] = sigm(v1[j]); }
;                     } else {
; #pragma unroll
;                         for (int j = 0; j < 4; ++j) s += v0[j] * v0[j] + v1[j] * v1[j];
;                     }
;                     *(u32x4*)(dst + (size_t)row * ldc + bj * 128) = pk8(v0, v1);
	v_cvt_pk_bf16_f32 v176, v178, v179
	v_cvt_pk_bf16_f32 v177, v180, v181
	global_store_dwordx4 v[148:149], v[174:177], off offset:256
	v_lshl_add_u64 v[148:149], v[148:149], 0, s[98:99]
	v_mul_f32_e32 v166, 0xbfb8aa3b, v12
	v_mul_f32_e32 v167, 0xbfb8aa3b, v13
	v_mul_f32_e32 v168, 0xbfb8aa3b, v14
	v_mul_f32_e32 v169, 0xbfb8aa3b, v15
	v_mul_f32_e32 v170, 0xbfb8aa3b, v8
	v_mul_f32_e32 v171, 0xbfb8aa3b, v9
	v_mul_f32_e32 v172, 0xbfb8aa3b, v10
	v_mul_f32_e32 v173, 0xbfb8aa3b, v11
	v_exp_f32_e32 v166, v166
	v_exp_f32_e32 v167, v167
	v_exp_f32_e32 v168, v168
	v_exp_f32_e32 v169, v169
	v_exp_f32_e32 v170, v170
	v_exp_f32_e32 v171, v171
	v_exp_f32_e32 v172, v172
	v_exp_f32_e32 v173, v173
	v_add_f32_e32 v166, 1.0, v166
	v_add_f32_e32 v167, 1.0, v167
	v_add_f32_e32 v168, 1.0, v168
	v_add_f32_e32 v169, 1.0, v169
	v_add_f32_e32 v170, 1.0, v170
	v_add_f32_e32 v171, 1.0, v171
	v_add_f32_e32 v172, 1.0, v172
	v_add_f32_e32 v173, 1.0, v173
	v_rcp_f32_e32 v166, v166
	v_rcp_f32_e32 v167, v167
	v_rcp_f32_e32 v168, v168
	v_rcp_f32_e32 v169, v169
	v_rcp_f32_e32 v170, v170
	v_rcp_f32_e32 v171, v171
	v_rcp_f32_e32 v172, v172
	v_rcp_f32_e32 v173, v173
	s_nop 0
	v_cvt_pk_bf16_f32 v166, v166, v167
	v_cvt_pk_bf16_f32 v167, v168, v169
	v_cvt_pk_bf16_f32 v168, v170, v171
	v_cvt_pk_bf16_f32 v169, v172, v173
	global_store_dwordx4 v[148:149], v[166:169], off
	v_mul_f32_e32 v174, 0xbfb8aa3b, v4
	v_mul_f32_e32 v175, 0xbfb8aa3b, v5
	v_mul_f32_e32 v176, 0xbfb8aa3b, v6
	v_mul_f32_e32 v177, 0xbfb8aa3b, v7
	v_mul_f32_e32 v178, 0xbfb8aa3b, v0
	v_mul_f32_e32 v179, 0xbfb8aa3b, v1
	v_mul_f32_e32 v180, 0xbfb8aa3b, v2
	v_mul_f32_e32 v181, 0xbfb8aa3b, v3
	v_exp_f32_e32 v174, v174
	v_exp_f32_e32 v175, v175
	v_exp_f32_e32 v176, v176
	v_exp_f32_e32 v177, v177
	v_exp_f32_e32 v178, v178
	v_exp_f32_e32 v179, v179
	v_exp_f32_e32 v180, v180
	v_exp_f32_e32 v181, v181
	v_add_f32_e32 v174, 1.0, v174
	v_add_f32_e32 v175, 1.0, v175
	v_add_f32_e32 v176, 1.0, v176
	v_add_f32_e32 v177, 1.0, v177
	v_add_f32_e32 v178, 1.0, v178
	v_add_f32_e32 v179, 1.0, v179
	v_add_f32_e32 v180, 1.0, v180
	v_add_f32_e32 v181, 1.0, v181
	v_rcp_f32_e32 v174, v174
	v_rcp_f32_e32 v175, v175
	v_rcp_f32_e32 v176, v176
	v_rcp_f32_e32 v177, v177
	v_rcp_f32_e32 v178, v178
	v_rcp_f32_e32 v179, v179
	v_rcp_f32_e32 v180, v180
	v_rcp_f32_e32 v181, v181
	s_nop 0
	v_cvt_pk_bf16_f32 v174, v174, v175
	v_cvt_pk_bf16_f32 v175, v176, v177
	v_cvt_pk_bf16_f32 v176, v178, v179
	v_cvt_pk_bf16_f32 v177, v180, v181
	global_store_dwordx4 v[148:149], v[174:177], off offset:256
	s_branch .LBB0_802
.Lepi1_silu:
	v_add_u32_e32 v128, s2, v162
	v_ashrrev_i32_e32 v129, 31, v128
	v_lshl_add_u64 v[128:129], v[128:129], 1, s[8:9]
	s_lshl_b32 s98, s46, 5
	s_mov_b32 s99, 0
	s_mul_i32 s100, s46, 0xa0
	s_mov_b32 s101, 0
	v_mad_u64_u32 v[148:149], s[2:3], s46, v130, 0
	v_lshl_add_u64 v[148:149], v[148:149], 1, v[128:129]
	v_mul_f32_e32 v166, 0xbfb8aa3b, v124
	v_mul_f32_e32 v167, 0xbfb8aa3b, v125
	v_mul_f32_e32 v168, 0xbfb8aa3b, v126
	v_mul_f32_e32 v169, 0xbfb8aa3b, v127
	v_mul_f32_e32 v170, 0xbfb8aa3b, v120
	v_mul_f32_e32 v171, 0xbfb8aa3b, v121
	v_mul_f32_e32 v172, 0xbfb8aa3b, v122
	v_mul_f32_e32 v173, 0xbfb8aa3b, v123
	v_exp_f32_e32 v166, v166
	v_exp_f32_e32 v167, v167
	v_exp_f32_e32 v168, v168
	v_exp_f32_e32 v169, v169
	v_exp_f32_e32 v170, v170
	v_exp_f32_e32 v171, v171
	v_exp_f32_e32 v172, v172
	v_exp_f32_e32 v173, v173
	v_add_f32_e32 v166, 1.0, v166
	v_add_f32_e32 v167, 1.0, v167
	v_add_f32_e32 v168, 1.0, v168
	v_add_f32_e32 v169, 1.0, v169
	v_add_f32_e32 v170, 1.0, v170
	v_add_f32_e32 v171, 1.0, v171
	v_add_f32_e32 v172, 1.0, v172
	v_add_f32_e32 v173, 1.0, v173
	v_rcp_f32_e32 v166, v166
	v_rcp_f32_e32 v167, v167
	v_rcp_f32_e32 v168, v168
	v_rcp_f32_e32 v169, v169
	v_rcp_f32_e32 v170, v170
	v_rcp_f32_e32 v171, v171
	v_rcp_f32_e32 v172, v172
	v_rcp_f32_e32 v173, v173
	v_mul_f32_e32 v166, v124, v166
	v_mul_f32_e32 v167, v125, v167
	v_mul_f32_e32 v168, v126, v168
	v_mul_f32_e32 v169, v127, v169
	v_mul_f32_e32 v170, v120, v170
	v_mul_f32_e32 v171, v121, v171
	v_mul_f32_e32 v172, v122, v172
	v_mul_f32_e32 v173, v123, v173
	v_cvt_pk_bf16_f32 v166, v166, v167
	v_cvt_pk_bf16_f32 v167, v168, v169
	v_cvt_pk_bf16_f32 v168, v170, v171
	v_cvt_pk_bf16_f32 v169, v172, v173
	global_store_dwordx4 v[148:149], v[166:169], off
	v_mul_f32_e32 v174, 0xbfb8aa3b, v116
	v_mul_f32_e32 v175, 0xbfb8aa3b, v117
	v_mul_f32_e32 v176, 0xbfb8aa3b, v118
	v_mul_f32_e32 v177, 0xbfb8aa3b, v119
	v_mul_f32_e32 v178, 0xbfb8aa3b, v112
	v_mul_f32_e32 v179, 0xbfb8aa3b, v113
	v_mul_f32_e32 v180, 0xbfb8aa3b, v114
	v_mul_f32_e32 v181, 0xbfb8aa3b, v115
	v_exp_f32_e32 v174, v174
	v_exp_f32_e32 v175, v175
	v_exp_f32_e32 v176, v176
	v_exp_f32_e32 v177, v177
	v_exp_f32_e32 v178, v178
	v_exp_f32_e32 v179, v179
	v_exp_f32_e32 v180, v180
	v_exp_f32_e32 v181, v181
	v_add_f32_e32 v174, 1.0, v174
	v_add_f32_e32 v175, 1.0, v175
	v_add_f32_e32 v176, 1.0, v176
	v_add_f32_e32 v177, 1.0, v177
	v_add_f32_e32 v178, 1.0, v178
	v_add_f32_e32 v179, 1.0, v179
	v_add_f32_e32 v180, 1.0, v180
	v_add_f32_e32 v181, 1.0, v181
	v_rcp_f32_e32 v174, v174
	v_rcp_f32_e32 v175, v175
	v_rcp_f32_e32 v176, v176
	v_rcp_f32_e32 v177, v177
	v_rcp_f32_e32 v178, v178
	v_rcp_f32_e32 v179, v179
	v_rcp_f32_e32 v180, v180
	v_rcp_f32_e32 v181, v181
	v_mul_f32_e32 v174, v116, v174
	v_mul_f32_e32 v175, v117, v175
	v_mul_f32_e32 v176, v118, v176
	v_mul_f32_e32 v177, v119, v177
	v_mul_f32_e32 v178, v112, v178
	v_mul_f32_e32 v179, v113, v179
	v_mul_f32_e32 v180, v114, v180
	v_mul_f32_e32 v181, v115, v181
	v_cvt_pk_bf16_f32 v174, v174, v175
	v_cvt_pk_bf16_f32 v175, v176, v177
	v_cvt_pk_bf16_f32 v176, v178, v179
	v_cvt_pk_bf16_f32 v177, v180, v181
; __device__ __forceinline__ unsigned pk(float lo, float hi) { unsigned r; asm("s_nop 0\n\tv_cvt_pk_bf16_f32 %0, %1, %2" : "=v"(r) : "v"(lo), "v"(hi)); return r; }
; __device__ __forceinline__ float sigm(float v) { return __builtin_amdgcn_rcpf(1.f + __builtin_amdgcn_exp2f(-LOG2E * v)); }
; __device__ __forceinline__ float silu(float v) { return v * sigm(v); }
; __device__ __forceinline__ u32x4 pk8(const f32x4& a, const f32x4& b) { u32x4 w; w.x = pk(a[0], a[1]); w.y = pk(a[2], a[3]); w.z = pk(b[0], b[1]); w.w = pk(b[2], b[3]); return w; }
;     __device__ __forceinline__ void operator()(const f32x4 (&acc)[2][2][4][2], const pg8::Unit& u, int wr, int wc, int fr, int fq) const {
;     ...
;         dst += col + wc * 32 + 8 * fq;
; #pragma unroll
;         for (int ai = 0; ai < 2; ++ai)
; #pragma unroll
;             for (int m = 0; m < 4; ++m) {
;                 const int row = row0 + ai * 128 + m * 16; float s = 0.f;
; #pragma unroll
;                 for (int bj = 0; bj < 2; ++bj) {
;                     f32x4 v0 = acc[ai][bj][m][0], v1 = acc[ai][bj][m][1];
;                     if (act == 1) {
; #pragma unroll
;                         for (int j = 0; j < 4; ++j) { v0[j] = silu(v0[j]); v1[j] = silu(v1[j]); }
;                     } else if (act == 2) {
; #pragma unroll
;                         for (int j = 0; j < 4; ++j) { v0[j] = sigm(v0[j]); v1[j] = sigm(v1[j]); }
;                     } else {
; #pragma unroll
;                         for (int j = 0; j < 4; ++j) s += v0[j] * v0[j] + v1[j] * v1[j];
;                     }
;                     *(u32x4*)(dst + (size_t)row * ldc + bj * 128) = pk8(v0, v1);
	global_store_dwordx4 v[148:149], v[174:177], off offset:256
	v_lshl_add_u64 v[148:149], v[148:149], 0, s[98:99]
	v_mul_f32_e32 v166, 0xbfb8aa3b, v108
	v_mul_f32_e32 v167, 0xbfb8aa3b, v109
	v_mul_f32_e32 v168, 0xbfb8aa3b, v110
	v_mul_f32_e32 v169, 0xbfb8aa3b, v111
	v_mul_f32_e32 v170, 0xbfb8aa3b, v104
	v_mul_f32_e32 v171, 0xbfb8aa3b, v105
	v_mul_f32_e32 v172, 0xbfb8aa3b, v106
	v_mul_f32_e32 v173, 0xbfb8aa3b, v107
	v_exp_f32_e32 v166, v166
	v_exp_f32_e32 v167, v167
	v_exp_f32_e32 v168, v168
	v_exp_f32_e32 v169, v169
	v_exp_f32_e32 v170, v170
	v_exp_f32_e32 v171, v171
	v_exp_f32_e32 v172, v172
	v_exp_f32_e32 v173, v173
	v_add_f32_e32 v166, 1.0, v166
	v_add_f32_e32 v167, 1.0, v167
	v_add_f32_e32 v168, 1.0, v168
	v_add_f32_e32 v169, 1.0, v169
	v_add_f32_e32 v170, 1.0, v170
	v_add_f32_e32 v171, 1.0, v171
	v_add_f32_e32 v172, 1.0, v172
	v_add_f32_e32 v173, 1.0, v173
	v_rcp_f32_e32 v166, v166
	v_rcp_f32_e32 v167, v167
	v_rcp_f32_e32 v168, v168
	v_rcp_f32_e32 v169, v169
	v_rcp_f32_e32 v170, v170
	v_rcp_f32_e32 v171, v171
	v_rcp_f32_e32 v172, v172
	v_rcp_f32_e32 v173, v173
	v_mul_f32_e32 v166, v108, v166
	v_mul_f32_e32 v167, v109, v167
	v_mul_f32_e32 v168, v110, v168
	v_mul_f32_e32 v169, v111, v169
	v_mul_f32_e32 v170, v104, v170
	v_mul_f32_e32 v171, v105, v171
	v_mul_f32_e32 v172, v106, v172
	v_mul_f32_e32 v173, v107, v173
	v_cvt_pk_bf16_f32 v166, v166, v167
	v_cvt_pk_bf16_f32 v167, v168, v169
	v_cvt_pk_bf16_f32 v168, v170, v171
	v_cvt_pk_bf16_f32 v169, v172, v173
	global_store_dwordx4 v[148:149], v[166:169], off
	v_mul_f32_e32 v174, 0xbfb8aa3b, v100
	v_mul_f32_e32 v175, 0xbfb8aa3b, v101
	v_mul_f32_e32 v176, 0xbfb8aa3b, v102
	v_mul_f32_e32 v177, 0xbfb8aa3b, v103
	v_mul_f32_e32 v178, 0xbfb8aa3b, v96
	v_mul_f32_e32 v179, 0xbfb8aa3b, v97
	v_mul_f32_e32 v180, 0xbfb8aa3b, v98
	v_mul_f32_e32 v181, 0xbfb8aa3b, v99
	v_exp_f32_e32 v174, v174
	v_exp_f32_e32 v175, v175
	v_exp_f32_e32 v176, v176
	v_exp_f32_e32 v177, v177
	v_exp_f32_e32 v178, v178
	v_exp_f32_e32 v179, v179
	v_exp_f32_e32 v180, v180
	v_exp_f32_e32 v181, v181
	v_add_f32_e32 v174, 1.0, v174
	v_add_f32_e32 v175, 1.0, v175
	v_add_f32_e32 v176, 1.0, v176
	v_add_f32_e32 v177, 1.0, v177
	v_add_f32_e32 v178, 1.0, v178
	v_add_f32_e32 v179, 1.0, v179
	v_add_f32_e32 v180, 1.0, v180
	v_add_f32_e32 v181, 1.0, v181
	v_rcp_f32_e32 v174, v174
	v_rcp_f32_e32 v175, v175
	v_rcp_f32_e32 v176, v176
	v_rcp_f32_e32 v177, v177
	v_rcp_f32_e32 v178, v178
	v_rcp_f32_e32 v179, v179
	v_rcp_f32_e32 v180, v180
	v_rcp_f32_e32 v181, v181
	v_mul_f32_e32 v174, v100, v174
	v_mul_f32_e32 v175, v101, v175
	v_mul_f32_e32 v176, v102, v176
	v_mul_f32_e32 v177, v103, v177
	v_mul_f32_e32 v178, v96, v178
	v_mul_f32_e32 v179, v97, v179
	v_mul_f32_e32 v180, v98, v180
	v_mul_f32_e32 v181, v99, v181
	v_cvt_pk_bf16_f32 v174, v174, v175
	v_cvt_pk_bf16_f32 v175, v176, v177
	v_cvt_pk_bf16_f32 v176, v178, v179
	v_cvt_pk_bf16_f32 v177, v180, v181
	global_store_dwordx4 v[148:149], v[174:177], off offset:256
	v_lshl_add_u64 v[148:149], v[148:149], 0, s[98:99]
	v_mul_f32_e32 v166, 0xbfb8aa3b, v92
	v_mul_f32_e32 v167, 0xbfb8aa3b, v93
	v_mul_f32_e32 v168, 0xbfb8aa3b, v94
	v_mul_f32_e32 v169, 0xbfb8aa3b, v95
	v_mul_f32_e32 v170, 0xbfb8aa3b, v88
	v_mul_f32_e32 v171, 0xbfb8aa3b, v89
	v_mul_f32_e32 v172, 0xbfb8aa3b, v90
	v_mul_f32_e32 v173, 0xbfb8aa3b, v91
	v_exp_f32_e32 v166, v166
	v_exp_f32_e32 v167, v167
	v_exp_f32_e32 v168, v168
	v_exp_f32_e32 v169, v169
	v_exp_f32_e32 v170, v170
	v_exp_f32_e32 v171, v171
	v_exp_f32_e32 v172, v172
	v_exp_f32_e32 v173, v173
	v_add_f32_e32 v166, 1.0, v166
	v_add_f32_e32 v167, 1.0, v167
	v_add_f32_e32 v168, 1.0, v168
	v_add_f32_e32 v169, 1.0, v169
	v_add_f32_e32 v170, 1.0, v170
	v_add_f32_e32 v171, 1.0, v171
	v_add_f32_e32 v172, 1.0, v172
	v_add_f32_e32 v173, 1.0, v173
	v_rcp_f32_e32 v166, v166
	v_rcp_f32_e32 v167, v167
	v_rcp_f32_e32 v168, v168
	v_rcp_f32_e32 v169, v169
	v_rcp_f32_e32 v170, v170
	v_rcp_f32_e32 v171, v171
	v_rcp_f32_e32 v172, v172
	v_rcp_f32_e32 v173, v173
	v_mul_f32_e32 v166, v92, v166
	v_mul_f32_e32 v167, v93, v167
	v_mul_f32_e32 v168, v94, v168
	v_mul_f32_e32 v169, v95, v169
	v_mul_f32_e32 v170, v88, v170
	v_mul_f32_e32 v171, v89, v171
	v_mul_f32_e32 v172, v90, v172
	v_mul_f32_e32 v173, v91, v173
	v_cvt_pk_bf16_f32 v166, v166, v167
	v_cvt_pk_bf16_f32 v167, v168, v169
	v_cvt_pk_bf16_f32 v168, v170, v171
	v_cvt_pk_bf16_f32 v169, v172, v173
	global_store_dwordx4 v[148:149], v[166:169], off
	v_mul_f32_e32 v174, 0xbfb8aa3b, v84
	v_mul_f32_e32 v175, 0xbfb8aa3b, v85
	v_mul_f32_e32 v176, 0xbfb8aa3b, v86
	v_mul_f32_e32 v177, 0xbfb8aa3b, v87
	v_mul_f32_e32 v178, 0xbfb8aa3b, v80
	v_mul_f32_e32 v179, 0xbfb8aa3b, v81
	v_mul_f32_e32 v180, 0xbfb8aa3b, v82
	v_mul_f32_e32 v181, 0xbfb8aa3b, v83
	v_exp_f32_e32 v174, v174
	v_exp_f32_e32 v175, v175
	v_exp_f32_e32 v176, v176
	v_exp_f32_e32 v177, v177
	v_exp_f32_e32 v178, v178
	v_exp_f32_e32 v179, v179
	v_exp_f32_e32 v180, v180
	v_exp_f32_e32 v181, v181
	v_add_f32_e32 v174, 1.0, v174
	v_add_f32_e32 v175, 1.0, v175
	v_add_f32_e32 v176, 1.0, v176
	v_add_f32_e32 v177, 1.0, v177
	v_add_f32_e32 v178, 1.0, v178
	v_add_f32_e32 v179, 1.0, v179
	v_add_f32_e32 v180, 1.0, v180
	v_add_f32_e32 v181, 1.0, v181
	v_rcp_f32_e32 v174, v174
	v_rcp_f32_e32 v175, v175
	v_rcp_f32_e32 v176, v176
	v_rcp_f32_e32 v177, v177
	v_rcp_f32_e32 v178, v178
	v_rcp_f32_e32 v179, v179
	v_rcp_f32_e32 v180, v180
	v_rcp_f32_e32 v181, v181
	v_mul_f32_e32 v174, v84, v174
	v_mul_f32_e32 v175, v85, v175
	v_mul_f32_e32 v176, v86, v176
	v_mul_f32_e32 v177, v87, v177
	v_mul_f32_e32 v178, v80, v178
	v_mul_f32_e32 v179, v81, v179
	v_mul_f32_e32 v180, v82, v180
	v_mul_f32_e32 v181, v83, v181
	v_cvt_pk_bf16_f32 v174, v174, v175
; __device__ __forceinline__ unsigned pk(float lo, float hi) { unsigned r; asm("s_nop 0\n\tv_cvt_pk_bf16_f32 %0, %1, %2" : "=v"(r) : "v"(lo), "v"(hi)); return r; }
; __device__ __forceinline__ float sigm(float v) { return __builtin_amdgcn_rcpf(1.f + __builtin_amdgcn_exp2f(-LOG2E * v)); }
; __device__ __forceinline__ float silu(float v) { return v * sigm(v); }
; __device__ __forceinline__ u32x4 pk8(const f32x4& a, const f32x4& b) { u32x4 w; w.x = pk(a[0], a[1]); w.y = pk(a[2], a[3]); w.z = pk(b[0], b[1]); w.w = pk(b[2], b[3]); return w; }
;     __device__ __forceinline__ void operator()(const f32x4 (&acc)[2][2][4][2], const pg8::Unit& u, int wr, int wc, int fr, int fq) const {
;     ...
;         dst += col + wc * 32 + 8 * fq;
; #pragma unroll
;         for (int ai = 0; ai < 2; ++ai)
; #pragma unroll
;             for (int m = 0; m < 4; ++m) {
;                 const int row = row0 + ai * 128 + m * 16; float s = 0.f;
; #pragma unroll
;                 for (int bj = 0; bj < 2; ++bj) {
;                     f32x4 v0 = acc[ai][bj][m][0], v1 = acc[ai][bj][m][1];
;                     if (act == 1) {
; #pragma unroll
;                         for (int j = 0; j < 4; ++j) { v0[j] = silu(v0[j]); v1[j] = silu(v1[j]); }
;                     } else if (act == 2) {
; #pragma unroll
;                         for (int j = 0; j < 4; ++j) { v0[j] = sigm(v0[j]); v1[j] = sigm(v1[j]); }
;                     } else {
; #pragma unroll
;                         for (int j = 0; j < 4; ++j) s += v0[j] * v0[j] + v1[j] * v1[j];
;                     }
;                     *(u32x4*)(dst + (size_t)row * ldc + bj * 128) = pk8(v0, v1);
	v_cvt_pk_bf16_f32 v175, v176, v177
	v_cvt_pk_bf16_f32 v176, v178, v179
	v_cvt_pk_bf16_f32 v177, v180, v181
	global_store_dwordx4 v[148:149], v[174:177], off offset:256
	v_lshl_add_u64 v[148:149], v[148:149], 0, s[98:99]
	v_mul_f32_e32 v166, 0xbfb8aa3b, v76
	v_mul_f32_e32 v167, 0xbfb8aa3b, v77
	v_mul_f32_e32 v168, 0xbfb8aa3b, v78
	v_mul_f32_e32 v169, 0xbfb8aa3b, v79
	v_mul_f32_e32 v170, 0xbfb8aa3b, v72
	v_mul_f32_e32 v171, 0xbfb8aa3b, v73
	v_mul_f32_e32 v172, 0xbfb8aa3b, v74
	v_mul_f32_e32 v173, 0xbfb8aa3b, v75
	v_exp_f32_e32 v166, v166
	v_exp_f32_e32 v167, v167
	v_exp_f32_e32 v168, v168
	v_exp_f32_e32 v169, v169
	v_exp_f32_e32 v170, v170
	v_exp_f32_e32 v171, v171
	v_exp_f32_e32 v172, v172
	v_exp_f32_e32 v173, v173
	v_add_f32_e32 v166, 1.0, v166
	v_add_f32_e32 v167, 1.0, v167
	v_add_f32_e32 v168, 1.0, v168
	v_add_f32_e32 v169, 1.0, v169
	v_add_f32_e32 v170, 1.0, v170
	v_add_f32_e32 v171, 1.0, v171
	v_add_f32_e32 v172, 1.0, v172
	v_add_f32_e32 v173, 1.0, v173
	v_rcp_f32_e32 v166, v166
	v_rcp_f32_e32 v167, v167
	v_rcp_f32_e32 v168, v168
	v_rcp_f32_e32 v169, v169
	v_rcp_f32_e32 v170, v170
	v_rcp_f32_e32 v171, v171
	v_rcp_f32_e32 v172, v172
	v_rcp_f32_e32 v173, v173
	v_mul_f32_e32 v166, v76, v166
	v_mul_f32_e32 v167, v77, v167
	v_mul_f32_e32 v168, v78, v168
	v_mul_f32_e32 v169, v79, v169
	v_mul_f32_e32 v170, v72, v170
	v_mul_f32_e32 v171, v73, v171
	v_mul_f32_e32 v172, v74, v172
	v_mul_f32_e32 v173, v75, v173
	v_cvt_pk_bf16_f32 v166, v166, v167
	v_cvt_pk_bf16_f32 v167, v168, v169
	v_cvt_pk_bf16_f32 v168, v170, v171
	v_cvt_pk_bf16_f32 v169, v172, v173
	global_store_dwordx4 v[148:149], v[166:169], off
	v_mul_f32_e32 v174, 0xbfb8aa3b, v68
	v_mul_f32_e32 v175, 0xbfb8aa3b, v69
	v_mul_f32_e32 v176, 0xbfb8aa3b, v70
	v_mul_f32_e32 v177, 0xbfb8aa3b, v71
	v_mul_f32_e32 v178, 0xbfb8aa3b, v64
	v_mul_f32_e32 v179, 0xbfb8aa3b, v65
	v_mul_f32_e32 v180, 0xbfb8aa3b, v66
	v_mul_f32_e32 v181, 0xbfb8aa3b, v67
	v_exp_f32_e32 v174, v174
	v_exp_f32_e32 v175, v175
	v_exp_f32_e32 v176, v176
	v_exp_f32_e32 v177, v177
	v_exp_f32_e32 v178, v178
	v_exp_f32_e32 v179, v179
	v_exp_f32_e32 v180, v180
	v_exp_f32_e32 v181, v181
	v_add_f32_e32 v174, 1.0, v174
	v_add_f32_e32 v175, 1.0, v175
	v_add_f32_e32 v176, 1.0, v176
	v_add_f32_e32 v177, 1.0, v177
	v_add_f32_e32 v178, 1.0, v178
	v_add_f32_e32 v179, 1.0, v179
	v_add_f32_e32 v180, 1.0, v180
	v_add_f32_e32 v181, 1.0, v181
	v_rcp_f32_e32 v174, v174
	v_rcp_f32_e32 v175, v175
	v_rcp_f32_e32 v176, v176
	v_rcp_f32_e32 v177, v177
	v_rcp_f32_e32 v178, v178
	v_rcp_f32_e32 v179, v179
	v_rcp_f32_e32 v180, v180
	v_rcp_f32_e32 v181, v181
	v_mul_f32_e32 v174, v68, v174
	v_mul_f32_e32 v175, v69, v175
	v_mul_f32_e32 v176, v70, v176
	v_mul_f32_e32 v177, v71, v177
	v_mul_f32_e32 v178, v64, v178
	v_mul_f32_e32 v179, v65, v179
	v_mul_f32_e32 v180, v66, v180
	v_mul_f32_e32 v181, v67, v181
	v_cvt_pk_bf16_f32 v174, v174, v175
	v_cvt_pk_bf16_f32 v175, v176, v177
	v_cvt_pk_bf16_f32 v176, v178, v179
	v_cvt_pk_bf16_f32 v177, v180, v181
	global_store_dwordx4 v[148:149], v[174:177], off offset:256
	v_lshl_add_u64 v[148:149], v[148:149], 0, s[100:101]
	v_mul_f32_e32 v166, 0xbfb8aa3b, v60
	v_mul_f32_e32 v167, 0xbfb8aa3b, v61
	v_mul_f32_e32 v168, 0xbfb8aa3b, v62
	v_mul_f32_e32 v169, 0xbfb8aa3b, v63
	v_mul_f32_e32 v170, 0xbfb8aa3b, v56
	v_mul_f32_e32 v171, 0xbfb8aa3b, v57
	v_mul_f32_e32 v172, 0xbfb8aa3b, v58
	v_mul_f32_e32 v173, 0xbfb8aa3b, v59
	v_exp_f32_e32 v166, v166
	v_exp_f32_e32 v167, v167
	v_exp_f32_e32 v168, v168
	v_exp_f32_e32 v169, v169
	v_exp_f32_e32 v170, v170
	v_exp_f32_e32 v171, v171
	v_exp_f32_e32 v172, v172
	v_exp_f32_e32 v173, v173
	v_add_f32_e32 v166, 1.0, v166
	v_add_f32_e32 v167, 1.0, v167
	v_add_f32_e32 v168, 1.0, v168
	v_add_f32_e32 v169, 1.0, v169
	v_add_f32_e32 v170, 1.0, v170
	v_add_f32_e32 v171, 1.0, v171
	v_add_f32_e32 v172, 1.0, v172
	v_add_f32_e32 v173, 1.0, v173
	v_rcp_f32_e32 v166, v166
	v_rcp_f32_e32 v167, v167
	v_rcp_f32_e32 v168, v168
	v_rcp_f32_e32 v169, v169
	v_rcp_f32_e32 v170, v170
	v_rcp_f32_e32 v171, v171
	v_rcp_f32_e32 v172, v172
	v_rcp_f32_e32 v173, v173
	v_mul_f32_e32 v166, v60, v166
	v_mul_f32_e32 v167, v61, v167
	v_mul_f32_e32 v168, v62, v168
	v_mul_f32_e32 v169, v63, v169
	v_mul_f32_e32 v170, v56, v170
	v_mul_f32_e32 v171, v57, v171
	v_mul_f32_e32 v172, v58, v172
	v_mul_f32_e32 v173, v59, v173
	v_cvt_pk_bf16_f32 v166, v166, v167
	v_cvt_pk_bf16_f32 v167, v168, v169
	v_cvt_pk_bf16_f32 v168, v170, v171
	v_cvt_pk_bf16_f32 v169, v172, v173
	global_store_dwordx4 v[148:149], v[166:169], off
	v_mul_f32_e32 v174, 0xbfb8aa3b, v52
	v_mul_f32_e32 v175, 0xbfb8aa3b, v53
	v_mul_f32_e32 v176, 0xbfb8aa3b, v54
	v_mul_f32_e32 v177, 0xbfb8aa3b, v55
	v_mul_f32_e32 v178, 0xbfb8aa3b, v48
	v_mul_f32_e32 v179, 0xbfb8aa3b, v49
	v_mul_f32_e32 v180, 0xbfb8aa3b, v50
	v_mul_f32_e32 v181, 0xbfb8aa3b, v51
	v_exp_f32_e32 v174, v174
	v_exp_f32_e32 v175, v175
	v_exp_f32_e32 v176, v176
	v_exp_f32_e32 v177, v177
	v_exp_f32_e32 v178, v178
	v_exp_f32_e32 v179, v179
	v_exp_f32_e32 v180, v180
	v_exp_f32_e32 v181, v181
	v_add_f32_e32 v174, 1.0, v174
	v_add_f32_e32 v175, 1.0, v175
	v_add_f32_e32 v176, 1.0, v176
	v_add_f32_e32 v177, 1.0, v177
	v_add_f32_e32 v178, 1.0, v178
	v_add_f32_e32 v179, 1.0, v179
	v_add_f32_e32 v180, 1.0, v180
	v_add_f32_e32 v181, 1.0, v181
	v_rcp_f32_e32 v174, v174
	v_rcp_f32_e32 v175, v175
	v_rcp_f32_e32 v176, v176
	v_rcp_f32_e32 v177, v177
	v_rcp_f32_e32 v178, v178
	v_rcp_f32_e32 v179, v179
	v_rcp_f32_e32 v180, v180
	v_rcp_f32_e32 v181, v181
	v_mul_f32_e32 v174, v52, v174
	v_mul_f32_e32 v175, v53, v175
	v_mul_f32_e32 v176, v54, v176
	v_mul_f32_e32 v177, v55, v177
	v_mul_f32_e32 v178, v48, v178
	v_mul_f32_e32 v179, v49, v179
; __device__ __forceinline__ u32x4 pk8(const f32x4& a, const f32x4& b) { u32x4 w; w.x = pk(a[0], a[1]); w.y = pk(a[2], a[3]); w.z = pk(b[0], b[1]); w.w = pk(b[2], b[3]); return w; }
; __device__ __forceinline__ float sigm(float v) { return __builtin_amdgcn_rcpf(1.f + __builtin_amdgcn_exp2f(-LOG2E * v)); }
; __device__ __forceinline__ float silu(float v) { return v * sigm(v); }
;     __device__ __forceinline__ void operator()(const f32x4 (&acc)[2][2][4][2], const pg8::Unit& u, int wr, int wc, int fr, int fq) const {
;     ...
;                     if (act == 1) {
; #pragma unroll
;                         for (int j = 0; j < 4; ++j) { v0[j] = silu(v0[j]); v1[j] = silu(v1[j]); }
;                     } else if (act == 2) {
; #pragma unroll
;                         for (int j = 0; j < 4; ++j) { v0[j] = sigm(v0[j]); v1[j] = sigm(v1[j]); }
;                     } else {
; #pragma unroll
;                         for (int j = 0; j < 4; ++j) s += v0[j] * v0[j] + v1[j] * v1[j];
;                     }
;                     *(u32x4*)(dst + (size_t)row * ldc + bj * 128) = pk8(v0, v1);
	v_mul_f32_e32 v180, v50, v180
	v_mul_f32_e32 v181, v51, v181
	v_cvt_pk_bf16_f32 v174, v174, v175
	v_cvt_pk_bf16_f32 v175, v176, v177
	v_cvt_pk_bf16_f32 v176, v178, v179
	v_cvt_pk_bf16_f32 v177, v180, v181
	global_store_dwordx4 v[148:149], v[174:177], off offset:256
	v_lshl_add_u64 v[148:149], v[148:149], 0, s[98:99]
	v_mul_f32_e32 v166, 0xbfb8aa3b, v44
	v_mul_f32_e32 v167, 0xbfb8aa3b, v45
	v_mul_f32_e32 v168, 0xbfb8aa3b, v46
	v_mul_f32_e32 v169, 0xbfb8aa3b, v47
	v_mul_f32_e32 v170, 0xbfb8aa3b, v40
	v_mul_f32_e32 v171, 0xbfb8aa3b, v41
	v_mul_f32_e32 v172, 0xbfb8aa3b, v42
	v_mul_f32_e32 v173, 0xbfb8aa3b, v43
	v_exp_f32_e32 v166, v166
	v_exp_f32_e32 v167, v167
	v_exp_f32_e32 v168, v168
	v_exp_f32_e32 v169, v169
	v_exp_f32_e32 v170, v170
	v_exp_f32_e32 v171, v171
	v_exp_f32_e32 v172, v172
	v_exp_f32_e32 v173, v173
	v_add_f32_e32 v166, 1.0, v166
	v_add_f32_e32 v167, 1.0, v167
	v_add_f32_e32 v168, 1.0, v168
	v_add_f32_e32 v169, 1.0, v169
	v_add_f32_e32 v170, 1.0, v170
	v_add_f32_e32 v171, 1.0, v171
	v_add_f32_e32 v172, 1.0, v172
	v_add_f32_e32 v173, 1.0, v173
	v_rcp_f32_e32 v166, v166
	v_rcp_f32_e32 v167, v167
	v_rcp_f32_e32 v168, v168
	v_rcp_f32_e32 v169, v169
	v_rcp_f32_e32 v170, v170
	v_rcp_f32_e32 v171, v171
	v_rcp_f32_e32 v172, v172
	v_rcp_f32_e32 v173, v173
	v_mul_f32_e32 v166, v44, v166
	v_mul_f32_e32 v167, v45, v167
	v_mul_f32_e32 v168, v46, v168
	v_mul_f32_e32 v169, v47, v169
	v_mul_f32_e32 v170, v40, v170
	v_mul_f32_e32 v171, v41, v171
	v_mul_f32_e32 v172, v42, v172
	v_mul_f32_e32 v173, v43, v173
	v_cvt_pk_bf16_f32 v166, v166, v167
	v_cvt_pk_bf16_f32 v167, v168, v169
	v_cvt_pk_bf16_f32 v168, v170, v171
	v_cvt_pk_bf16_f32 v169, v172, v173
	global_store_dwordx4 v[148:149], v[166:169], off
	v_mul_f32_e32 v174, 0xbfb8aa3b, v36
	v_mul_f32_e32 v175, 0xbfb8aa3b, v37
	v_mul_f32_e32 v176, 0xbfb8aa3b, v38
	v_mul_f32_e32 v177, 0xbfb8aa3b, v39
	v_mul_f32_e32 v178, 0xbfb8aa3b, v32
	v_mul_f32_e32 v179, 0xbfb8aa3b, v33
	v_mul_f32_e32 v180, 0xbfb8aa3b, v34
	v_mul_f32_e32 v181, 0xbfb8aa3b, v35
	v_exp_f32_e32 v174, v174
	v_exp_f32_e32 v175, v175
	v_exp_f32_e32 v176, v176
	v_exp_f32_e32 v177, v177
	v_exp_f32_e32 v178, v178
	v_exp_f32_e32 v179, v179
	v_exp_f32_e32 v180, v180
	v_exp_f32_e32 v181, v181
	v_add_f32_e32 v174, 1.0, v174
	v_add_f32_e32 v175, 1.0, v175
	v_add_f32_e32 v176, 1.0, v176
	v_add_f32_e32 v177, 1.0, v177
	v_add_f32_e32 v178, 1.0, v178
	v_add_f32_e32 v179, 1.0, v179
	v_add_f32_e32 v180, 1.0, v180
	v_add_f32_e32 v181, 1.0, v181
	v_rcp_f32_e32 v174, v174
	v_rcp_f32_e32 v175, v175
	v_rcp_f32_e32 v176, v176
	v_rcp_f32_e32 v177, v177
	v_rcp_f32_e32 v178, v178
	v_rcp_f32_e32 v179, v179
	v_rcp_f32_e32 v180, v180
	v_rcp_f32_e32 v181, v181
	v_mul_f32_e32 v174, v36, v174
	v_mul_f32_e32 v175, v37, v175
	v_mul_f32_e32 v176, v38, v176
	v_mul_f32_e32 v177, v39, v177
	v_mul_f32_e32 v178, v32, v178
	v_mul_f32_e32 v179, v33, v179
	v_mul_f32_e32 v180, v34, v180
	v_mul_f32_e32 v181, v35, v181
	v_cvt_pk_bf16_f32 v174, v174, v175
	v_cvt_pk_bf16_f32 v175, v176, v177
	v_cvt_pk_bf16_f32 v176, v178, v179
	v_cvt_pk_bf16_f32 v177, v180, v181
	global_store_dwordx4 v[148:149], v[174:177], off offset:256
	v_lshl_add_u64 v[148:149], v[148:149], 0, s[98:99]
	v_mul_f32_e32 v166, 0xbfb8aa3b, v28
	v_mul_f32_e32 v167, 0xbfb8aa3b, v29
	v_mul_f32_e32 v168, 0xbfb8aa3b, v30
	v_mul_f32_e32 v169, 0xbfb8aa3b, v31
	v_mul_f32_e32 v170, 0xbfb8aa3b, v24
	v_mul_f32_e32 v171, 0xbfb8aa3b, v25
	v_mul_f32_e32 v172, 0xbfb8aa3b, v26
	v_mul_f32_e32 v173, 0xbfb8aa3b, v27
	v_exp_f32_e32 v166, v166
	v_exp_f32_e32 v167, v167
	v_exp_f32_e32 v168, v168
	v_exp_f32_e32 v169, v169
	v_exp_f32_e32 v170, v170
	v_exp_f32_e32 v171, v171
	v_exp_f32_e32 v172, v172
	v_exp_f32_e32 v173, v173
	v_add_f32_e32 v166, 1.0, v166
	v_add_f32_e32 v167, 1.0, v167
	v_add_f32_e32 v168, 1.0, v168
	v_add_f32_e32 v169, 1.0, v169
	v_add_f32_e32 v170, 1.0, v170
	v_add_f32_e32 v171, 1.0, v171
	v_add_f32_e32 v172, 1.0, v172
	v_add_f32_e32 v173, 1.0, v173
	v_rcp_f32_e32 v166, v166
	v_rcp_f32_e32 v167, v167
	v_rcp_f32_e32 v168, v168
	v_rcp_f32_e32 v169, v169
	v_rcp_f32_e32 v170, v170
	v_rcp_f32_e32 v171, v171
	v_rcp_f32_e32 v172, v172
	v_rcp_f32_e32 v173, v173
	v_mul_f32_e32 v166, v28, v166
	v_mul_f32_e32 v167, v29, v167
	v_mul_f32_e32 v168, v30, v168
	v_mul_f32_e32 v169, v31, v169
	v_mul_f32_e32 v170, v24, v170
	v_mul_f32_e32 v171, v25, v171
	v_mul_f32_e32 v172, v26, v172
	v_mul_f32_e32 v173, v27, v173
	v_cvt_pk_bf16_f32 v166, v166, v167
; __device__ __forceinline__ u32x4 pk8(const f32x4& a, const f32x4& b) { u32x4 w; w.x = pk(a[0], a[1]); w.y = pk(a[2], a[3]); w.z = pk(b[0], b[1]); w.w = pk(b[2], b[3]); return w; }
; __device__ __forceinline__ float sigm(float v) { return __builtin_amdgcn_rcpf(1.f + __builtin_amdgcn_exp2f(-LOG2E * v)); }
; __device__ __forceinline__ float silu(float v) { return v * sigm(v); }
;     __device__ __forceinline__ void operator()(const f32x4 (&acc)[2][2][4][2], const pg8::Unit& u, int wr, int wc, int fr, int fq) const {
;     ...
;                     if (act == 1) {
; #pragma unroll
;                         for (int j = 0; j < 4; ++j) { v0[j] = silu(v0[j]); v1[j] = silu(v1[j]); }
;                     } else if (act == 2) {
; #pragma unroll
;                         for (int j = 0; j < 4; ++j) { v0[j] = sigm(v0[j]); v1[j] = sigm(v1[j]); }
;                     } else {
; #pragma unroll
;                         for (int j = 0; j < 4; ++j) s += v0[j] * v0[j] + v1[j] * v1[j];
;                     }
;                     *(u32x4*)(dst + (size_t)row * ldc + bj * 128) = pk8(v0, v1);
	v_cvt_pk_bf16_f32 v167, v168, v169
	v_cvt_pk_bf16_f32 v168, v170, v171
	v_cvt_pk_bf16_f32 v169, v172, v173
	global_store_dwordx4 v[148:149], v[166:169], off
	v_mul_f32_e32 v174, 0xbfb8aa3b, v20
	v_mul_f32_e32 v175, 0xbfb8aa3b, v21
	v_mul_f32_e32 v176, 0xbfb8aa3b, v22
	v_mul_f32_e32 v177, 0xbfb8aa3b, v23
	v_mul_f32_e32 v178, 0xbfb8aa3b, v16
	v_mul_f32_e32 v179, 0xbfb8aa3b, v17
	v_mul_f32_e32 v180, 0xbfb8aa3b, v18
	v_mul_f32_e32 v181, 0xbfb8aa3b, v19
	v_exp_f32_e32 v174, v174
	v_exp_f32_e32 v175, v175
	v_exp_f32_e32 v176, v176
	v_exp_f32_e32 v177, v177
	v_exp_f32_e32 v178, v178
	v_exp_f32_e32 v179, v179
	v_exp_f32_e32 v180, v180
	v_exp_f32_e32 v181, v181
	v_add_f32_e32 v174, 1.0, v174
	v_add_f32_e32 v175, 1.0, v175
	v_add_f32_e32 v176, 1.0, v176
	v_add_f32_e32 v177, 1.0, v177
	v_add_f32_e32 v178, 1.0, v178
	v_add_f32_e32 v179, 1.0, v179
	v_add_f32_e32 v180, 1.0, v180
	v_add_f32_e32 v181, 1.0, v181
	v_rcp_f32_e32 v174, v174
	v_rcp_f32_e32 v175, v175
	v_rcp_f32_e32 v176, v176
	v_rcp_f32_e32 v177, v177
	v_rcp_f32_e32 v178, v178
	v_rcp_f32_e32 v179, v179
	v_rcp_f32_e32 v180, v180
	v_rcp_f32_e32 v181, v181
	v_mul_f32_e32 v174, v20, v174
	v_mul_f32_e32 v175, v21, v175
	v_mul_f32_e32 v176, v22, v176
	v_mul_f32_e32 v177, v23, v177
	v_mul_f32_e32 v178, v16, v178
	v_mul_f32_e32 v179, v17, v179
	v_mul_f32_e32 v180, v18, v180
	v_mul_f32_e32 v181, v19, v181
	v_cvt_pk_bf16_f32 v174, v174, v175
	v_cvt_pk_bf16_f32 v175, v176, v177
	v_cvt_pk_bf16_f32 v176, v178, v179
	v_cvt_pk_bf16_f32 v177, v180, v181
	global_store_dwordx4 v[148:149], v[174:177], off offset:256
	v_lshl_add_u64 v[148:149], v[148:149], 0, s[98:99]
	v_mul_f32_e32 v166, 0xbfb8aa3b, v12
	v_mul_f32_e32 v167, 0xbfb8aa3b, v13
	v_mul_f32_e32 v168, 0xbfb8aa3b, v14
	v_mul_f32_e32 v169, 0xbfb8aa3b, v15
	v_mul_f32_e32 v170, 0xbfb8aa3b, v8
	v_mul_f32_e32 v171, 0xbfb8aa3b, v9
	v_mul_f32_e32 v172, 0xbfb8aa3b, v10
	v_mul_f32_e32 v173, 0xbfb8aa3b, v11
	v_exp_f32_e32 v166, v166
	v_exp_f32_e32 v167, v167
	v_exp_f32_e32 v168, v168
	v_exp_f32_e32 v169, v169
	v_exp_f32_e32 v170, v170
	v_exp_f32_e32 v171, v171
	v_exp_f32_e32 v172, v172
	v_exp_f32_e32 v173, v173
	v_add_f32_e32 v166, 1.0, v166
	v_add_f32_e32 v167, 1.0, v167
	v_add_f32_e32 v168, 1.0, v168
	v_add_f32_e32 v169, 1.0, v169
	v_add_f32_e32 v170, 1.0, v170
	v_add_f32_e32 v171, 1.0, v171
	v_add_f32_e32 v172, 1.0, v172
	v_add_f32_e32 v173, 1.0, v173
	v_rcp_f32_e32 v166, v166
	v_rcp_f32_e32 v167, v167
	v_rcp_f32_e32 v168, v168
	v_rcp_f32_e32 v169, v169
	v_rcp_f32_e32 v170, v170
	v_rcp_f32_e32 v171, v171
	v_rcp_f32_e32 v172, v172
	v_rcp_f32_e32 v173, v173
	v_mul_f32_e32 v166, v12, v166
	v_mul_f32_e32 v167, v13, v167
	v_mul_f32_e32 v168, v14, v168
	v_mul_f32_e32 v169, v15, v169
	v_mul_f32_e32 v170, v8, v170
	v_mul_f32_e32 v171, v9, v171
	v_mul_f32_e32 v172, v10, v172
	v_mul_f32_e32 v173, v11, v173
	v_cvt_pk_bf16_f32 v166, v166, v167
	v_cvt_pk_bf16_f32 v167, v168, v169
	v_cvt_pk_bf16_f32 v168, v170, v171
	v_cvt_pk_bf16_f32 v169, v172, v173
	global_store_dwordx4 v[148:149], v[166:169], off
	v_mul_f32_e32 v174, 0xbfb8aa3b, v4
	v_mul_f32_e32 v175, 0xbfb8aa3b, v5
	v_mul_f32_e32 v176, 0xbfb8aa3b, v6
	v_mul_f32_e32 v177, 0xbfb8aa3b, v7
	v_mul_f32_e32 v178, 0xbfb8aa3b, v0
	v_mul_f32_e32 v179, 0xbfb8aa3b, v1
	v_mul_f32_e32 v180, 0xbfb8aa3b, v2
	v_mul_f32_e32 v181, 0xbfb8aa3b, v3
	v_exp_f32_e32 v174, v174
	v_exp_f32_e32 v175, v175
	v_exp_f32_e32 v176, v176
	v_exp_f32_e32 v177, v177
	v_exp_f32_e32 v178, v178
	v_exp_f32_e32 v179, v179
	v_exp_f32_e32 v180, v180
	v_exp_f32_e32 v181, v181
	v_add_f32_e32 v174, 1.0, v174
	v_add_f32_e32 v175, 1.0, v175
	v_add_f32_e32 v176, 1.0, v176
	v_add_f32_e32 v177, 1.0, v177
	v_add_f32_e32 v178, 1.0, v178
	v_add_f32_e32 v179, 1.0, v179
	v_add_f32_e32 v180, 1.0, v180
	v_add_f32_e32 v181, 1.0, v181
	v_rcp_f32_e32 v174, v174
	v_rcp_f32_e32 v175, v175
	v_rcp_f32_e32 v176, v176
	v_rcp_f32_e32 v177, v177
	v_rcp_f32_e32 v178, v178
	v_rcp_f32_e32 v179, v179
	v_rcp_f32_e32 v180, v180
	v_rcp_f32_e32 v181, v181
	v_mul_f32_e32 v174, v4, v174
	v_mul_f32_e32 v175, v5, v175
	v_mul_f32_e32 v176, v6, v176
	v_mul_f32_e32 v177, v7, v177
	v_mul_f32_e32 v178, v0, v178
	v_mul_f32_e32 v179, v1, v179
	v_mul_f32_e32 v180, v2, v180
	v_mul_f32_e32 v181, v3, v181
	v_cvt_pk_bf16_f32 v174, v174, v175
	v_cvt_pk_bf16_f32 v175, v176, v177
	v_cvt_pk_bf16_f32 v176, v178, v179
	v_cvt_pk_bf16_f32 v177, v180, v181
	global_store_dwordx4 v[148:149], v[174:177], off offset:256
	s_branch .LBB0_802
